# e30 mirrored: static s_setprio 1 for waves 0-3 in the GEMM K-loops (flips removed)
# baseline (speedup 1.0000x reference)
; template <class Epi, class Sched, bool ALIGN_EPI = false, bool SP2 = false>
; __device__ __forceinline__ void gemm_phase(PG8_LAS unsigned char* lds, const Gemm g, const Sched& S, const Epi& E) {
;     ...
;         const bool has_next = S.next(ui + 1, nxt);
;         const char* nA = has_next ? PG8_UA(nxt) : cA; const char* nB = has_next ? PG8_UB(nxt) : cB;
;     ...
; #pragma unroll
;         for (int a = 0; a < 2; ++a)
; #pragma unroll
;             for (int b = 0; b < 2; ++b)
; #pragma unroll
;                 for (int m = 0; m < 4; ++m)
; #pragma unroll
;                     for (int n = 0; n < 2; ++n) acc[a][b][m][n] = (f32x4){0.f, 0.f, 0.f, 0.f};
.LBB0_203:
	s_ashr_i32 s43, s42, 31
	s_lshl_b64 s[4:5], s[42:43], 20
	s_add_u32 s48, s67, s4
	s_addc_u32 s49, s77, s5
	s_and_b64 s[4:5], s[38:39], exec
	s_cselect_b32 s4, s49, s37
	s_cselect_b32 s5, s48, s36
	s_ashr_i32 s21, s20, 31
	s_lshl_b64 s[6:7], s[20:21], 20
	s_add_u32 s50, s0, s6
	s_addc_u32 s51, s1, s7
	s_and_b64 s[6:7], s[38:39], exec
	s_cselect_b32 s6, s51, s57
	s_cselect_b32 s7, s50, s56
	s_add_u32 s36, s36, 0x80080
	s_addc_u32 s37, s37, 0
	s_add_u32 s21, s56, 0x100
	v_mov_b32_e32 v4, 0
	s_addc_u32 s41, s57, 0
	s_mov_b32 s43, -2
	v_mov_b32_e32 v5, v4
	v_mov_b32_e32 v6, v4
	v_mov_b32_e32 v7, v4
	v_mov_b32_e32 v8, v4
	v_mov_b32_e32 v9, v4
	v_mov_b32_e32 v10, v4
	v_mov_b32_e32 v11, v4
	v_mov_b32_e32 v20, v4
	v_mov_b32_e32 v21, v4
	v_mov_b32_e32 v22, v4
	v_mov_b32_e32 v23, v4
	v_mov_b32_e32 v24, v4
	v_mov_b32_e32 v25, v4
	v_mov_b32_e32 v26, v4
	v_mov_b32_e32 v27, v4
	v_mov_b32_e32 v36, v4
	v_mov_b32_e32 v37, v4
	v_mov_b32_e32 v38, v4
	v_mov_b32_e32 v39, v4
	v_mov_b32_e32 v40, v4
	v_mov_b32_e32 v41, v4
	v_mov_b32_e32 v42, v4
	v_mov_b32_e32 v43, v4
	v_mov_b32_e32 v52, v4
	v_mov_b32_e32 v53, v4
	v_mov_b32_e32 v54, v4
	v_mov_b32_e32 v55, v4
	v_mov_b32_e32 v56, v4
	v_mov_b32_e32 v57, v4
	v_mov_b32_e32 v58, v4
	v_mov_b32_e32 v59, v4
	v_mov_b32_e32 v12, v4
	v_mov_b32_e32 v13, v4
	v_mov_b32_e32 v14, v4
	v_mov_b32_e32 v15, v4
	v_mov_b32_e32 v16, v4
	v_mov_b32_e32 v17, v4
	v_mov_b32_e32 v18, v4
	v_mov_b32_e32 v19, v4
	v_mov_b32_e32 v28, v4
	v_mov_b32_e32 v29, v4
	v_mov_b32_e32 v30, v4
	v_mov_b32_e32 v31, v4
	v_mov_b32_e32 v32, v4
	v_mov_b32_e32 v33, v4
	v_mov_b32_e32 v34, v4
	v_mov_b32_e32 v35, v4
	v_mov_b32_e32 v44, v4
	v_mov_b32_e32 v45, v4
	v_mov_b32_e32 v46, v4
	v_mov_b32_e32 v47, v4
	v_mov_b32_e32 v48, v4
	v_mov_b32_e32 v49, v4
	v_mov_b32_e32 v50, v4
	v_mov_b32_e32 v51, v4
	v_mov_b32_e32 v60, v4
	v_mov_b32_e32 v61, v4
	v_mov_b32_e32 v62, v4
	v_mov_b32_e32 v63, v4
	v_mov_b32_e32 v64, v4
	v_mov_b32_e32 v65, v4
	v_mov_b32_e32 v66, v4
	v_mov_b32_e32 v67, v4
	v_mov_b32_e32 v68, v4
	v_mov_b32_e32 v69, v4
	v_mov_b32_e32 v70, v4
	v_mov_b32_e32 v71, v4
	v_mov_b32_e32 v72, v4
	v_mov_b32_e32 v73, v4
	v_mov_b32_e32 v74, v4
	v_mov_b32_e32 v75, v4
	v_mov_b32_e32 v84, v4
	v_mov_b32_e32 v85, v4
	v_mov_b32_e32 v86, v4
	v_mov_b32_e32 v87, v4
	v_mov_b32_e32 v88, v4
	v_mov_b32_e32 v89, v4
	v_mov_b32_e32 v90, v4
	v_mov_b32_e32 v91, v4
	v_mov_b32_e32 v100, v4
	v_mov_b32_e32 v101, v4
	v_mov_b32_e32 v102, v4
	v_mov_b32_e32 v103, v4
	v_mov_b32_e32 v104, v4
	v_mov_b32_e32 v105, v4
	v_mov_b32_e32 v106, v4
	v_mov_b32_e32 v107, v4
	v_mov_b32_e32 v116, v4
	v_mov_b32_e32 v117, v4
	v_mov_b32_e32 v118, v4
	v_mov_b32_e32 v119, v4
	v_mov_b32_e32 v120, v4
	v_mov_b32_e32 v121, v4
	v_mov_b32_e32 v122, v4
	v_mov_b32_e32 v123, v4
	v_mov_b32_e32 v76, v4
	v_mov_b32_e32 v77, v4
	v_mov_b32_e32 v78, v4
	v_mov_b32_e32 v79, v4
	v_mov_b32_e32 v80, v4
	v_mov_b32_e32 v81, v4
	v_mov_b32_e32 v82, v4
	v_mov_b32_e32 v83, v4
	v_mov_b32_e32 v92, v4
	v_mov_b32_e32 v93, v4
	v_mov_b32_e32 v94, v4
	v_mov_b32_e32 v95, v4
	v_mov_b32_e32 v96, v4
	v_mov_b32_e32 v97, v4
	v_mov_b32_e32 v98, v4
	v_mov_b32_e32 v99, v4
	v_mov_b32_e32 v108, v4
	v_mov_b32_e32 v109, v4
	v_mov_b32_e32 v110, v4
	v_mov_b32_e32 v111, v4
	v_mov_b32_e32 v112, v4
	v_mov_b32_e32 v113, v4
	v_mov_b32_e32 v114, v4
	v_mov_b32_e32 v115, v4
	v_mov_b32_e32 v124, v4
	v_mov_b32_e32 v125, v4
	v_mov_b32_e32 v126, v4
	v_mov_b32_e32 v127, v4
	v_mov_b32_e32 v128, v4
	v_mov_b32_e32 v129, v4
	v_mov_b32_e32 v130, v4
	v_mov_b32_e32 v131, v4
	s_nop 0
	v_readfirstlane_b32 s98, v0
	s_nop 3
	s_lshr_b32 s98, s98, 6
	s_cmp_ge_u32 s98, 4
	s_cbranch_scc1 .Lprio_g0
	s_setprio 1

; template <class Epi, class Sched, bool ALIGN_EPI = false, bool SP2 = false>
; __device__ __forceinline__ void gemm_phase(PG8_LAS unsigned char* lds, const Gemm g, const Sched& S, const Epi& E) {
;     ...
;         const bool has_next = S.next(ui + 1, nxt);
;         const char* nA = has_next ? PG8_UA(nxt) : cA; const char* nB = has_next ? PG8_UB(nxt) : cB;
;     ...
; #pragma unroll
;         for (int a = 0; a < 2; ++a)
; #pragma unroll
;             for (int b = 0; b < 2; ++b)
; #pragma unroll
;                 for (int m = 0; m < 4; ++m)
; #pragma unroll
;                     for (int n = 0; n < 2; ++n) acc[a][b][m][n] = (f32x4){0.f, 0.f, 0.f, 0.f};
.LBB0_597:
	s_ashr_i32 s49, s48, 31
	s_lshl_b64 s[4:5], s[48:49], 20
	s_add_u32 s50, s67, s4
	s_addc_u32 s51, s77, s5
	s_and_b64 s[4:5], s[40:41], exec
	s_cselect_b32 s4, s51, s57
	s_cselect_b32 s5, s50, s56
	s_ashr_i32 s47, s46, 31
	s_lshl_b64 s[6:7], s[46:47], 20
	s_add_u32 s52, s12, s6
	s_addc_u32 s53, s13, s7
	s_and_b64 s[6:7], s[40:41], exec
	s_cselect_b32 s6, s53, s59
	s_cselect_b32 s7, s52, s58
	s_add_u32 s56, s56, 0x80080
	s_addc_u32 s57, s57, 0
	s_add_u32 s19, s58, 0x100
	v_mov_b32_e32 v4, 0
	s_addc_u32 s37, s59, 0
	s_mov_b32 s47, -2
	s_waitcnt lgkmcnt(0)
	v_mov_b32_e32 v5, v4
	v_mov_b32_e32 v6, v4
	v_mov_b32_e32 v7, v4
	v_mov_b32_e32 v8, v4
	v_mov_b32_e32 v9, v4
	v_mov_b32_e32 v10, v4
	v_mov_b32_e32 v11, v4
	v_mov_b32_e32 v20, v4
	v_mov_b32_e32 v21, v4
	v_mov_b32_e32 v22, v4
	v_mov_b32_e32 v23, v4
	v_mov_b32_e32 v24, v4
	v_mov_b32_e32 v25, v4
	v_mov_b32_e32 v26, v4
	v_mov_b32_e32 v27, v4
	v_mov_b32_e32 v36, v4
	v_mov_b32_e32 v37, v4
	v_mov_b32_e32 v38, v4
	v_mov_b32_e32 v39, v4
	v_mov_b32_e32 v40, v4
	v_mov_b32_e32 v41, v4
	v_mov_b32_e32 v42, v4
	v_mov_b32_e32 v43, v4
	v_mov_b32_e32 v52, v4
	v_mov_b32_e32 v53, v4
	v_mov_b32_e32 v54, v4
	v_mov_b32_e32 v55, v4
	v_mov_b32_e32 v56, v4
	v_mov_b32_e32 v57, v4
	v_mov_b32_e32 v58, v4
	v_mov_b32_e32 v59, v4
	v_mov_b32_e32 v12, v4
	v_mov_b32_e32 v13, v4
	v_mov_b32_e32 v14, v4
	v_mov_b32_e32 v15, v4
	v_mov_b32_e32 v16, v4
	v_mov_b32_e32 v17, v4
	v_mov_b32_e32 v18, v4
	v_mov_b32_e32 v19, v4
	v_mov_b32_e32 v28, v4
	v_mov_b32_e32 v29, v4
	v_mov_b32_e32 v30, v4
	v_mov_b32_e32 v31, v4
	v_mov_b32_e32 v32, v4
	v_mov_b32_e32 v33, v4
	v_mov_b32_e32 v34, v4
	v_mov_b32_e32 v35, v4
	v_mov_b32_e32 v44, v4
	v_mov_b32_e32 v45, v4
	v_mov_b32_e32 v46, v4
	v_mov_b32_e32 v47, v4
	v_mov_b32_e32 v48, v4
	v_mov_b32_e32 v49, v4
	v_mov_b32_e32 v50, v4
	v_mov_b32_e32 v51, v4
	v_mov_b32_e32 v60, v4
	v_mov_b32_e32 v61, v4
	v_mov_b32_e32 v62, v4
	v_mov_b32_e32 v63, v4
	v_mov_b32_e32 v64, v4
	v_mov_b32_e32 v65, v4
	v_mov_b32_e32 v66, v4
	v_mov_b32_e32 v67, v4
	v_mov_b32_e32 v68, v4
	v_mov_b32_e32 v69, v4
	v_mov_b32_e32 v70, v4
	v_mov_b32_e32 v71, v4
	v_mov_b32_e32 v72, v4
	v_mov_b32_e32 v73, v4
	v_mov_b32_e32 v74, v4
	v_mov_b32_e32 v75, v4
	v_mov_b32_e32 v84, v4
	v_mov_b32_e32 v85, v4
	v_mov_b32_e32 v86, v4
	v_mov_b32_e32 v87, v4
	v_mov_b32_e32 v88, v4
	v_mov_b32_e32 v89, v4
	v_mov_b32_e32 v90, v4
	v_mov_b32_e32 v91, v4
	v_mov_b32_e32 v100, v4
	v_mov_b32_e32 v101, v4
	v_mov_b32_e32 v102, v4
	v_mov_b32_e32 v103, v4
	v_mov_b32_e32 v104, v4
	v_mov_b32_e32 v105, v4
	v_mov_b32_e32 v106, v4
	v_mov_b32_e32 v107, v4
	v_mov_b32_e32 v116, v4
	v_mov_b32_e32 v117, v4
	v_mov_b32_e32 v118, v4
	v_mov_b32_e32 v119, v4
	v_mov_b32_e32 v120, v4
	v_mov_b32_e32 v121, v4
	v_mov_b32_e32 v122, v4
	v_mov_b32_e32 v123, v4
	v_mov_b32_e32 v76, v4
	v_mov_b32_e32 v77, v4
	v_mov_b32_e32 v78, v4
	v_mov_b32_e32 v79, v4
	v_mov_b32_e32 v80, v4
	v_mov_b32_e32 v81, v4
	v_mov_b32_e32 v82, v4
	v_mov_b32_e32 v83, v4
	v_mov_b32_e32 v92, v4
	v_mov_b32_e32 v93, v4
	v_mov_b32_e32 v94, v4
	v_mov_b32_e32 v95, v4
	v_mov_b32_e32 v96, v4
	v_mov_b32_e32 v97, v4
	v_mov_b32_e32 v98, v4
	v_mov_b32_e32 v99, v4
	v_mov_b32_e32 v108, v4
	v_mov_b32_e32 v109, v4
	v_mov_b32_e32 v110, v4
	v_mov_b32_e32 v111, v4
	v_mov_b32_e32 v112, v4
	v_mov_b32_e32 v113, v4
	v_mov_b32_e32 v114, v4
	v_mov_b32_e32 v115, v4
	v_mov_b32_e32 v124, v4
	v_mov_b32_e32 v125, v4
	v_mov_b32_e32 v126, v4
	v_mov_b32_e32 v127, v4
	v_mov_b32_e32 v128, v4
	v_mov_b32_e32 v129, v4
	v_mov_b32_e32 v130, v4
	v_mov_b32_e32 v131, v4
	v_readfirstlane_b32 s98, v0
	s_nop 3
	s_lshr_b32 s98, s98, 6
	s_cmp_ge_u32 s98, 4
	s_cbranch_scc1 .Lprio_g1
	s_setprio 1

; template <class Epi, class Sched, bool ALIGN_EPI = false, bool SP2 = false>
; __device__ __forceinline__ void gemm_phase(PG8_LAS unsigned char* lds, const Gemm g, const Sched& S, const Epi& E) {
;     ...
;         const bool has_next = S.next(ui + 1, nxt);
;         const char* nA = has_next ? PG8_UA(nxt) : cA; const char* nB = has_next ? PG8_UB(nxt) : cB;
;     ...
; #pragma unroll
;         for (int a = 0; a < 2; ++a)
; #pragma unroll
;             for (int b = 0; b < 2; ++b)
; #pragma unroll
;                 for (int m = 0; m < 4; ++m)
; #pragma unroll
;                     for (int n = 0; n < 2; ++n) acc[a][b][m][n] = (f32x4){0.f, 0.f, 0.f, 0.f};
.LBB0_1759:
	s_ashr_i32 s53, s52, 31
	s_lshl_b64 s[4:5], s[52:53], 18
	s_add_u32 s64, s18, s4
	s_addc_u32 s65, s19, s5
	s_and_b64 s[4:5], s[42:43], exec
	s_cselect_b32 s4, s65, s67
	s_cselect_b32 s5, s64, s66
	s_add_u32 s42, s62, 0x80080
	s_addc_u32 s43, s63, 0
	s_add_u32 s6, s66, 0x100
	v_mov_b32_e32 v4, 0
	s_addc_u32 s7, s67, 0
	s_mov_b32 s21, -2
	s_waitcnt lgkmcnt(0)
	v_mov_b32_e32 v5, v4
	v_mov_b32_e32 v6, v4
	v_mov_b32_e32 v7, v4
	v_mov_b32_e32 v8, v4
	v_mov_b32_e32 v9, v4
	v_mov_b32_e32 v10, v4
	v_mov_b32_e32 v11, v4
	v_mov_b32_e32 v20, v4
	v_mov_b32_e32 v21, v4
	v_mov_b32_e32 v22, v4
	v_mov_b32_e32 v23, v4
	v_mov_b32_e32 v24, v4
	v_mov_b32_e32 v25, v4
	v_mov_b32_e32 v26, v4
	v_mov_b32_e32 v27, v4
	v_mov_b32_e32 v36, v4
	v_mov_b32_e32 v37, v4
	v_mov_b32_e32 v38, v4
	v_mov_b32_e32 v39, v4
	v_mov_b32_e32 v40, v4
	v_mov_b32_e32 v41, v4
	v_mov_b32_e32 v42, v4
	v_mov_b32_e32 v43, v4
	v_mov_b32_e32 v52, v4
	v_mov_b32_e32 v53, v4
	v_mov_b32_e32 v54, v4
	v_mov_b32_e32 v55, v4
	v_mov_b32_e32 v56, v4
	v_mov_b32_e32 v57, v4
	v_mov_b32_e32 v58, v4
	v_mov_b32_e32 v59, v4
	v_mov_b32_e32 v12, v4
	v_mov_b32_e32 v13, v4
	v_mov_b32_e32 v14, v4
	v_mov_b32_e32 v15, v4
	v_mov_b32_e32 v16, v4
	v_mov_b32_e32 v17, v4
	v_mov_b32_e32 v18, v4
	v_mov_b32_e32 v19, v4
	v_mov_b32_e32 v28, v4
	v_mov_b32_e32 v29, v4
	v_mov_b32_e32 v30, v4
	v_mov_b32_e32 v31, v4
	v_mov_b32_e32 v32, v4
	v_mov_b32_e32 v33, v4
	v_mov_b32_e32 v34, v4
	v_mov_b32_e32 v35, v4
	v_mov_b32_e32 v44, v4
	v_mov_b32_e32 v45, v4
	v_mov_b32_e32 v46, v4
	v_mov_b32_e32 v47, v4
	v_mov_b32_e32 v48, v4
	v_mov_b32_e32 v49, v4
	v_mov_b32_e32 v50, v4
	v_mov_b32_e32 v51, v4
	v_mov_b32_e32 v60, v4
	v_mov_b32_e32 v61, v4
	v_mov_b32_e32 v62, v4
	v_mov_b32_e32 v63, v4
	v_mov_b32_e32 v64, v4
	v_mov_b32_e32 v65, v4
	v_mov_b32_e32 v66, v4
	v_mov_b32_e32 v67, v4
	v_mov_b32_e32 v68, v4
	v_mov_b32_e32 v69, v4
	v_mov_b32_e32 v70, v4
	v_mov_b32_e32 v71, v4
	v_mov_b32_e32 v72, v4
	v_mov_b32_e32 v73, v4
	v_mov_b32_e32 v74, v4
	v_mov_b32_e32 v75, v4
	v_mov_b32_e32 v100, v4
	v_mov_b32_e32 v101, v4
	v_mov_b32_e32 v102, v4
	v_mov_b32_e32 v103, v4
	v_mov_b32_e32 v104, v4
	v_mov_b32_e32 v105, v4
	v_mov_b32_e32 v106, v4
	v_mov_b32_e32 v107, v4
	v_mov_b32_e32 v116, v4
	v_mov_b32_e32 v117, v4
	v_mov_b32_e32 v118, v4
	v_mov_b32_e32 v119, v4
	v_mov_b32_e32 v120, v4
	v_mov_b32_e32 v121, v4
	v_mov_b32_e32 v122, v4
	v_mov_b32_e32 v123, v4
	v_mov_b32_e32 v132, v4
	v_mov_b32_e32 v133, v4
	v_mov_b32_e32 v134, v4
	v_mov_b32_e32 v135, v4
	v_mov_b32_e32 v136, v4
	v_mov_b32_e32 v137, v4
	v_mov_b32_e32 v138, v4
	v_mov_b32_e32 v139, v4
	v_mov_b32_e32 v92, v4
	v_mov_b32_e32 v93, v4
	v_mov_b32_e32 v94, v4
	v_mov_b32_e32 v95, v4
	v_mov_b32_e32 v96, v4
	v_mov_b32_e32 v97, v4
	v_mov_b32_e32 v98, v4
	v_mov_b32_e32 v99, v4
	v_mov_b32_e32 v108, v4
	v_mov_b32_e32 v109, v4
	v_mov_b32_e32 v110, v4
	v_mov_b32_e32 v111, v4
	v_mov_b32_e32 v112, v4
	v_mov_b32_e32 v113, v4
	v_mov_b32_e32 v114, v4
	v_mov_b32_e32 v115, v4
	v_mov_b32_e32 v124, v4
	v_mov_b32_e32 v125, v4
	v_mov_b32_e32 v126, v4
	v_mov_b32_e32 v127, v4
	v_mov_b32_e32 v128, v4
	v_mov_b32_e32 v129, v4
	v_mov_b32_e32 v130, v4
	v_mov_b32_e32 v131, v4
	v_mov_b32_e32 v140, v4
	v_mov_b32_e32 v141, v4
	v_mov_b32_e32 v142, v4
	v_mov_b32_e32 v143, v4
	v_mov_b32_e32 v144, v4
	v_mov_b32_e32 v145, v4
	v_mov_b32_e32 v146, v4
	v_mov_b32_e32 v147, v4
	s_nop 0
	s_nop 0
	v_readfirstlane_b32 s98, v0
	s_nop 3
	s_lshr_b32 s98, s98, 6
	s_cmp_ge_u32 s98, 4
	s_cbranch_scc1 .Lprio_g2
	s_setprio 1

; template <class Epi, class Sched, bool ALIGN_EPI = false, bool SP2 = false>
; __device__ __forceinline__ void gemm_phase(PG8_LAS unsigned char* lds, const Gemm g, const Sched& S, const Epi& E) {
;     ...
;         const bool has_next = S.next(ui + 1, nxt);
;         const char* nA = has_next ? PG8_UA(nxt) : cA; const char* nB = has_next ? PG8_UB(nxt) : cB;
;     ...
; #pragma unroll
;         for (int a = 0; a < 2; ++a)
; #pragma unroll
;             for (int b = 0; b < 2; ++b)
; #pragma unroll
;                 for (int m = 0; m < 4; ++m)
; #pragma unroll
;                     for (int n = 0; n < 2; ++n) acc[a][b][m][n] = (f32x4){0.f, 0.f, 0.f, 0.f};
.LBB0_1885:
	s_ashr_i32 s53, s52, 31
	s_lshl_b64 s[4:5], s[52:53], 20
	s_add_u32 s56, s78, s4
	s_addc_u32 s57, s79, s5
	s_and_b64 s[4:5], s[38:39], exec
	s_cselect_b32 s3, s57, s37
	s_cselect_b32 s4, s56, s36
	s_ashr_i32 s21, s20, 31
	s_lshl_b64 s[6:7], s[20:21], 20
	s_add_u32 s58, s46, s6
	s_addc_u32 s59, s47, s7
	s_and_b64 s[6:7], s[38:39], exec
	s_cselect_b32 s5, s59, s43
	s_cselect_b32 s6, s58, s42
	s_add_u32 s36, s36, 0x80080
	s_addc_u32 s37, s37, 0
	s_add_u32 s7, s42, 0x100
	v_mov_b32_e32 v4, 0
	s_addc_u32 s21, s43, 0
	s_mov_b32 s41, -2
	v_mov_b32_e32 v5, v4
	v_mov_b32_e32 v6, v4
	v_mov_b32_e32 v7, v4
	v_mov_b32_e32 v8, v4
	v_mov_b32_e32 v9, v4
	v_mov_b32_e32 v10, v4
	v_mov_b32_e32 v11, v4
	v_mov_b32_e32 v20, v4
	v_mov_b32_e32 v21, v4
	v_mov_b32_e32 v22, v4
	v_mov_b32_e32 v23, v4
	v_mov_b32_e32 v28, v4
	v_mov_b32_e32 v29, v4
	v_mov_b32_e32 v30, v4
	v_mov_b32_e32 v31, v4
	v_mov_b32_e32 v52, v4
	v_mov_b32_e32 v53, v4
	v_mov_b32_e32 v54, v4
	v_mov_b32_e32 v55, v4
	v_mov_b32_e32 v56, v4
	v_mov_b32_e32 v57, v4
	v_mov_b32_e32 v58, v4
	v_mov_b32_e32 v59, v4
	v_mov_b32_e32 v68, v4
	v_mov_b32_e32 v69, v4
	v_mov_b32_e32 v70, v4
	v_mov_b32_e32 v71, v4
	v_mov_b32_e32 v72, v4
	v_mov_b32_e32 v73, v4
	v_mov_b32_e32 v74, v4
	v_mov_b32_e32 v75, v4
	v_mov_b32_e32 v12, v4
	v_mov_b32_e32 v13, v4
	v_mov_b32_e32 v14, v4
	v_mov_b32_e32 v15, v4
	v_mov_b32_e32 v16, v4
	v_mov_b32_e32 v17, v4
	v_mov_b32_e32 v18, v4
	v_mov_b32_e32 v19, v4
	v_mov_b32_e32 v40, v4
	v_mov_b32_e32 v41, v4
	v_mov_b32_e32 v42, v4
	v_mov_b32_e32 v43, v4
	v_mov_b32_e32 v48, v4
	v_mov_b32_e32 v49, v4
	v_mov_b32_e32 v50, v4
	v_mov_b32_e32 v51, v4
	v_mov_b32_e32 v60, v4
	v_mov_b32_e32 v61, v4
	v_mov_b32_e32 v62, v4
	v_mov_b32_e32 v63, v4
	v_mov_b32_e32 v64, v4
	v_mov_b32_e32 v65, v4
	v_mov_b32_e32 v66, v4
	v_mov_b32_e32 v67, v4
	v_mov_b32_e32 v76, v4
	v_mov_b32_e32 v77, v4
	v_mov_b32_e32 v78, v4
	v_mov_b32_e32 v79, v4
	v_mov_b32_e32 v80, v4
	v_mov_b32_e32 v81, v4
	v_mov_b32_e32 v82, v4
	v_mov_b32_e32 v83, v4
	v_mov_b32_e32 v84, v4
	v_mov_b32_e32 v85, v4
	v_mov_b32_e32 v86, v4
	v_mov_b32_e32 v87, v4
	v_mov_b32_e32 v88, v4
	v_mov_b32_e32 v89, v4
	v_mov_b32_e32 v90, v4
	v_mov_b32_e32 v91, v4
	v_mov_b32_e32 v100, v4
	v_mov_b32_e32 v101, v4
	v_mov_b32_e32 v102, v4
	v_mov_b32_e32 v103, v4
	v_mov_b32_e32 v104, v4
	v_mov_b32_e32 v105, v4
	v_mov_b32_e32 v106, v4
	v_mov_b32_e32 v107, v4
	v_mov_b32_e32 v116, v4
	v_mov_b32_e32 v117, v4
	v_mov_b32_e32 v118, v4
	v_mov_b32_e32 v119, v4
	v_mov_b32_e32 v120, v4
	v_mov_b32_e32 v121, v4
	v_mov_b32_e32 v122, v4
	v_mov_b32_e32 v123, v4
	v_mov_b32_e32 v132, v4
	v_mov_b32_e32 v133, v4
	v_mov_b32_e32 v134, v4
	v_mov_b32_e32 v135, v4
	v_mov_b32_e32 v136, v4
	v_mov_b32_e32 v137, v4
	v_mov_b32_e32 v138, v4
	v_mov_b32_e32 v139, v4
	v_mov_b32_e32 v92, v4
	v_mov_b32_e32 v93, v4
	v_mov_b32_e32 v94, v4
	v_mov_b32_e32 v95, v4
	v_mov_b32_e32 v96, v4
	v_mov_b32_e32 v97, v4
	v_mov_b32_e32 v98, v4
	v_mov_b32_e32 v99, v4
	v_mov_b32_e32 v108, v4
	v_mov_b32_e32 v109, v4
	v_mov_b32_e32 v110, v4
	v_mov_b32_e32 v111, v4
	v_mov_b32_e32 v112, v4
	v_mov_b32_e32 v113, v4
	v_mov_b32_e32 v114, v4
	v_mov_b32_e32 v115, v4
	v_mov_b32_e32 v124, v4
	v_mov_b32_e32 v125, v4
	v_mov_b32_e32 v126, v4
	v_mov_b32_e32 v127, v4
	v_mov_b32_e32 v128, v4
	v_mov_b32_e32 v129, v4
	v_mov_b32_e32 v130, v4
	v_mov_b32_e32 v131, v4
	v_mov_b32_e32 v140, v4
	v_mov_b32_e32 v141, v4
	v_mov_b32_e32 v142, v4
	v_mov_b32_e32 v143, v4
	v_mov_b32_e32 v144, v4
	v_mov_b32_e32 v145, v4
	v_mov_b32_e32 v146, v4
	v_mov_b32_e32 v147, v4
	s_nop 0
	v_readfirstlane_b32 s98, v0
	s_nop 3
	s_lshr_b32 s98, s98, 6
	s_cmp_ge_u32 s98, 4
	s_cbranch_scc1 .Lprio_g3
	s_setprio 1

; template <class Epi, class Sched, bool ALIGN_EPI = false, bool SP2 = false>
; __device__ __forceinline__ void gemm_phase(PG8_LAS unsigned char* lds, const Gemm g, const Sched& S, const Epi& E) {
;     ...
;         const bool has_next = S.next(ui + 1, nxt);
;         const char* nA = has_next ? PG8_UA(nxt) : cA; const char* nB = has_next ? PG8_UB(nxt) : cB;
;     ...
; #pragma unroll
;         for (int a = 0; a < 2; ++a)
; #pragma unroll
;             for (int b = 0; b < 2; ++b)
; #pragma unroll
;                 for (int m = 0; m < 4; ++m)
; #pragma unroll
;                     for (int n = 0; n < 2; ++n) acc[a][b][m][n] = (f32x4){0.f, 0.f, 0.f, 0.f};
.LBB0_2661:
	s_ashr_i32 s45, s44, 31
	s_lshl_b64 s[4:5], s[44:45], 20
	s_add_u32 s46, s64, s4
	s_addc_u32 s47, s65, s5
	s_and_b64 s[4:5], s[38:39], exec
	s_cselect_b32 s4, s47, s51
	s_cselect_b32 s5, s46, s50
	s_ashr_i32 s43, s42, 31
	s_lshl_b64 s[6:7], s[42:43], 20
	s_add_u32 s48, s12, s6
	s_addc_u32 s49, s13, s7
	s_and_b64 s[6:7], s[38:39], exec
	s_cselect_b32 s6, s49, s53
	s_cselect_b32 s7, s48, s52
	s_add_u32 s50, s50, 0x80080
	s_addc_u32 s51, s51, 0
	s_add_u32 s43, s52, 0x100
	v_mov_b32_e32 v4, 0
	s_addc_u32 s45, s53, 0
	s_mov_b32 s70, -2
	v_mov_b32_e32 v5, v4
	v_mov_b32_e32 v6, v4
	v_mov_b32_e32 v7, v4
	v_mov_b32_e32 v8, v4
	v_mov_b32_e32 v9, v4
	v_mov_b32_e32 v10, v4
	v_mov_b32_e32 v11, v4
	v_mov_b32_e32 v20, v4
	v_mov_b32_e32 v21, v4
	v_mov_b32_e32 v22, v4
	v_mov_b32_e32 v23, v4
	v_mov_b32_e32 v24, v4
	v_mov_b32_e32 v25, v4
	v_mov_b32_e32 v26, v4
	v_mov_b32_e32 v27, v4
	v_mov_b32_e32 v36, v4
	v_mov_b32_e32 v37, v4
	v_mov_b32_e32 v38, v4
	v_mov_b32_e32 v39, v4
	v_mov_b32_e32 v40, v4
	v_mov_b32_e32 v41, v4
	v_mov_b32_e32 v42, v4
	v_mov_b32_e32 v43, v4
	v_mov_b32_e32 v52, v4
	v_mov_b32_e32 v53, v4
	v_mov_b32_e32 v54, v4
	v_mov_b32_e32 v55, v4
	v_mov_b32_e32 v56, v4
	v_mov_b32_e32 v57, v4
	v_mov_b32_e32 v58, v4
	v_mov_b32_e32 v59, v4
	v_mov_b32_e32 v12, v4
	v_mov_b32_e32 v13, v4
	v_mov_b32_e32 v14, v4
	v_mov_b32_e32 v15, v4
	v_mov_b32_e32 v16, v4
	v_mov_b32_e32 v17, v4
	v_mov_b32_e32 v18, v4
	v_mov_b32_e32 v19, v4
	v_mov_b32_e32 v28, v4
	v_mov_b32_e32 v29, v4
	v_mov_b32_e32 v30, v4
	v_mov_b32_e32 v31, v4
	v_mov_b32_e32 v32, v4
	v_mov_b32_e32 v33, v4
	v_mov_b32_e32 v34, v4
	v_mov_b32_e32 v35, v4
	v_mov_b32_e32 v44, v4
	v_mov_b32_e32 v45, v4
	v_mov_b32_e32 v46, v4
	v_mov_b32_e32 v47, v4
	v_mov_b32_e32 v48, v4
	v_mov_b32_e32 v49, v4
	v_mov_b32_e32 v50, v4
	v_mov_b32_e32 v51, v4
	v_mov_b32_e32 v60, v4
	v_mov_b32_e32 v61, v4
	v_mov_b32_e32 v62, v4
	v_mov_b32_e32 v63, v4
	v_mov_b32_e32 v64, v4
	v_mov_b32_e32 v65, v4
	v_mov_b32_e32 v66, v4
	v_mov_b32_e32 v67, v4
	v_mov_b32_e32 v68, v4
	v_mov_b32_e32 v69, v4
	v_mov_b32_e32 v70, v4
	v_mov_b32_e32 v71, v4
	v_mov_b32_e32 v72, v4
	v_mov_b32_e32 v73, v4
	v_mov_b32_e32 v74, v4
	v_mov_b32_e32 v75, v4
	v_mov_b32_e32 v84, v4
	v_mov_b32_e32 v85, v4
	v_mov_b32_e32 v86, v4
	v_mov_b32_e32 v87, v4
	v_mov_b32_e32 v88, v4
	v_mov_b32_e32 v89, v4
	v_mov_b32_e32 v90, v4
	v_mov_b32_e32 v91, v4
	v_mov_b32_e32 v100, v4
	v_mov_b32_e32 v101, v4
	v_mov_b32_e32 v102, v4
	v_mov_b32_e32 v103, v4
	v_mov_b32_e32 v104, v4
	v_mov_b32_e32 v105, v4
	v_mov_b32_e32 v106, v4
	v_mov_b32_e32 v107, v4
	v_mov_b32_e32 v116, v4
	v_mov_b32_e32 v117, v4
	v_mov_b32_e32 v118, v4
	v_mov_b32_e32 v119, v4
	v_mov_b32_e32 v120, v4
	v_mov_b32_e32 v121, v4
	v_mov_b32_e32 v122, v4
	v_mov_b32_e32 v123, v4
	v_mov_b32_e32 v76, v4
	v_mov_b32_e32 v77, v4
	v_mov_b32_e32 v78, v4
	v_mov_b32_e32 v79, v4
	v_mov_b32_e32 v80, v4
	v_mov_b32_e32 v81, v4
	v_mov_b32_e32 v82, v4
	v_mov_b32_e32 v83, v4
	v_mov_b32_e32 v92, v4
	v_mov_b32_e32 v93, v4
	v_mov_b32_e32 v94, v4
	v_mov_b32_e32 v95, v4
	v_mov_b32_e32 v96, v4
	v_mov_b32_e32 v97, v4
	v_mov_b32_e32 v98, v4
	v_mov_b32_e32 v99, v4
	v_mov_b32_e32 v108, v4
	v_mov_b32_e32 v109, v4
	v_mov_b32_e32 v110, v4
	v_mov_b32_e32 v111, v4
	v_mov_b32_e32 v112, v4
	v_mov_b32_e32 v113, v4
	v_mov_b32_e32 v114, v4
	v_mov_b32_e32 v115, v4
	v_mov_b32_e32 v124, v4
	v_mov_b32_e32 v125, v4
	v_mov_b32_e32 v126, v4
	v_mov_b32_e32 v127, v4
	v_mov_b32_e32 v128, v4
	v_mov_b32_e32 v129, v4
	v_mov_b32_e32 v130, v4
	v_mov_b32_e32 v131, v4
	s_nop 0
	s_nop 0
	s_nop 0
	s_nop 0
	s_nop 0
	s_nop 0
	s_nop 0
	s_nop 0
	s_nop 0
	s_nop 0
	s_nop 0
	s_nop 0
	s_nop 0
	s_nop 0
	s_nop 0
	v_readfirstlane_b32 s98, v0
	s_nop 3
	s_lshr_b32 s98, s98, 6
	s_cmp_ge_u32 s98, 4
	s_cbranch_scc1 .Lprio_g5
	s_setprio 1

; template <class Epi, class Sched, bool ALIGN_EPI = false, bool SP2 = false>
; __device__ __forceinline__ void gemm_phase(PG8_LAS unsigned char* lds, const Gemm g, const Sched& S, const Epi& E) {
;     ...
; #pragma unroll
;         for (int a = 0; a < 2; ++a)
; #pragma unroll
;             for (int b = 0; b < 2; ++b)
; #pragma unroll
;                 for (int m = 0; m < 4; ++m)
; #pragma unroll
;                     for (int n = 0; n < 2; ++n) acc[a][b][m][n] = (f32x4){0.f, 0.f, 0.f, 0.f};
.LBB0_2769:
	s_add_u32 s4, s50, 0x100
	v_mov_b32_e32 v4, 0
	s_addc_u32 s5, s51, 0
	s_mov_b32 s6, -2
	s_waitcnt lgkmcnt(0)
	v_mov_b32_e32 v5, v4
	v_mov_b32_e32 v6, v4
	v_mov_b32_e32 v7, v4
	v_mov_b32_e32 v8, v4
	v_mov_b32_e32 v9, v4
	v_mov_b32_e32 v10, v4
	v_mov_b32_e32 v11, v4
	v_mov_b32_e32 v20, v4
	v_mov_b32_e32 v21, v4
	v_mov_b32_e32 v22, v4
	v_mov_b32_e32 v23, v4
	v_mov_b32_e32 v24, v4
	v_mov_b32_e32 v25, v4
	v_mov_b32_e32 v26, v4
	v_mov_b32_e32 v27, v4
	v_mov_b32_e32 v36, v4
	v_mov_b32_e32 v37, v4
	v_mov_b32_e32 v38, v4
	v_mov_b32_e32 v39, v4
	v_mov_b32_e32 v40, v4
	v_mov_b32_e32 v41, v4
	v_mov_b32_e32 v42, v4
	v_mov_b32_e32 v43, v4
	v_mov_b32_e32 v52, v4
	v_mov_b32_e32 v53, v4
	v_mov_b32_e32 v54, v4
	v_mov_b32_e32 v55, v4
	v_mov_b32_e32 v56, v4
	v_mov_b32_e32 v57, v4
	v_mov_b32_e32 v58, v4
	v_mov_b32_e32 v59, v4
	v_mov_b32_e32 v12, v4
	v_mov_b32_e32 v13, v4
	v_mov_b32_e32 v14, v4
	v_mov_b32_e32 v15, v4
	v_mov_b32_e32 v16, v4
	v_mov_b32_e32 v17, v4
	v_mov_b32_e32 v18, v4
	v_mov_b32_e32 v19, v4
	v_mov_b32_e32 v28, v4
	v_mov_b32_e32 v29, v4
	v_mov_b32_e32 v30, v4
	v_mov_b32_e32 v31, v4
	v_mov_b32_e32 v32, v4
	v_mov_b32_e32 v33, v4
	v_mov_b32_e32 v34, v4
	v_mov_b32_e32 v35, v4
	v_mov_b32_e32 v44, v4
	v_mov_b32_e32 v45, v4
	v_mov_b32_e32 v46, v4
	v_mov_b32_e32 v47, v4
	v_mov_b32_e32 v48, v4
	v_mov_b32_e32 v49, v4
	v_mov_b32_e32 v50, v4
	v_mov_b32_e32 v51, v4
	v_mov_b32_e32 v60, v4
	v_mov_b32_e32 v61, v4
	v_mov_b32_e32 v62, v4
	v_mov_b32_e32 v63, v4
	v_mov_b32_e32 v64, v4
	v_mov_b32_e32 v65, v4
	v_mov_b32_e32 v66, v4
	v_mov_b32_e32 v67, v4
	v_mov_b32_e32 v68, v4
	v_mov_b32_e32 v69, v4
	v_mov_b32_e32 v70, v4
	v_mov_b32_e32 v71, v4
	v_mov_b32_e32 v72, v4
	v_mov_b32_e32 v73, v4
	v_mov_b32_e32 v74, v4
	v_mov_b32_e32 v75, v4
	v_mov_b32_e32 v84, v4
	v_mov_b32_e32 v85, v4
	v_mov_b32_e32 v86, v4
	v_mov_b32_e32 v87, v4
	v_mov_b32_e32 v88, v4
	v_mov_b32_e32 v89, v4
	v_mov_b32_e32 v90, v4
	v_mov_b32_e32 v91, v4
	v_mov_b32_e32 v100, v4
	v_mov_b32_e32 v101, v4
	v_mov_b32_e32 v102, v4
	v_mov_b32_e32 v103, v4
	v_mov_b32_e32 v104, v4
	v_mov_b32_e32 v105, v4
	v_mov_b32_e32 v106, v4
	v_mov_b32_e32 v107, v4
	v_mov_b32_e32 v116, v4
	v_mov_b32_e32 v117, v4
	v_mov_b32_e32 v118, v4
	v_mov_b32_e32 v119, v4
	v_mov_b32_e32 v120, v4
	v_mov_b32_e32 v121, v4
	v_mov_b32_e32 v122, v4
	v_mov_b32_e32 v123, v4
	v_mov_b32_e32 v76, v4
	v_mov_b32_e32 v77, v4
	v_mov_b32_e32 v78, v4
	v_mov_b32_e32 v79, v4
	v_mov_b32_e32 v80, v4
	v_mov_b32_e32 v81, v4
	v_mov_b32_e32 v82, v4
	v_mov_b32_e32 v83, v4
	v_mov_b32_e32 v92, v4
	v_mov_b32_e32 v93, v4
	v_mov_b32_e32 v94, v4
	v_mov_b32_e32 v95, v4
	v_mov_b32_e32 v96, v4
	v_mov_b32_e32 v97, v4
	v_mov_b32_e32 v98, v4
	v_mov_b32_e32 v99, v4
	v_mov_b32_e32 v108, v4
	v_mov_b32_e32 v109, v4
	v_mov_b32_e32 v110, v4
	v_mov_b32_e32 v111, v4
	v_mov_b32_e32 v112, v4
	v_mov_b32_e32 v113, v4
	v_mov_b32_e32 v114, v4
	v_mov_b32_e32 v115, v4
	v_mov_b32_e32 v124, v4
	v_mov_b32_e32 v125, v4
	v_mov_b32_e32 v126, v4
	v_mov_b32_e32 v127, v4
	v_mov_b32_e32 v128, v4
	v_mov_b32_e32 v129, v4
	v_mov_b32_e32 v130, v4
	v_mov_b32_e32 v131, v4
	s_nop 0
	s_nop 0
	s_nop 0
	s_nop 0
	s_nop 0
	s_nop 0
	s_nop 0
	s_nop 0
	s_nop 0
	v_readfirstlane_b32 s98, v0
	s_nop 3
	s_lshr_b32 s98, s98, 6
	s_cmp_ge_u32 s98, 4
	s_cbranch_scc1 .Lprio_g6
	s_setprio 1
